# early L2 write-back kick at every grid barrier (wave 1 of each workgroup issues a non-blocking buffer_wbl2 on arrival); on top of v57
# baseline (speedup 1.0000x reference)
.LBB0_128:
	s_waitcnt vmcnt(0)
	s_waitcnt lgkmcnt(0)
	s_barrier
	v_readlane_b32 s96, v250, 44
	s_cmp_eq_u32 s96, 1
	s_cbranch_scc0 .Lewb_0
	buffer_wbl2 sc1
.Lewb_0:
	s_and_saveexec_b64 s[34:35], s[0:1]
	s_cbranch_execz .LBB0_173
	s_add_i32 s0, 0, 0x23f00
	v_mov_b32_e32 v0, s0
	s_waitcnt vmcnt(0) expcnt(0) lgkmcnt(0)
	ds_read_b32 v2, v0
	s_add_i32 s0, 0, 0x23f04
	v_mov_b32_e32 v0, s0
	ds_read_b32 v0, v0
	s_waitcnt lgkmcnt(1)
	v_cmp_ne_u32_e32 vcc, 0, v2
	s_cbranch_vccnz .LBB0_144
	v_readlane_b32 s2, v250, 0
	v_readlane_b32 s3, v250, 1
	s_load_dwordx2 s[0:1], s[2:3], 0x4
	s_add_u32 s2, s30, 0x1000
	s_addc_u32 s3, s31, 0
	s_add_u32 s4, s30, 0x1100
	s_addc_u32 s5, s31, 0
	s_add_u32 s6, s30, 0x1200
	s_addc_u32 s7, s31, 0
	s_add_u32 s8, s30, 0x1300
	s_waitcnt lgkmcnt(0)
	s_mul_i32 s18, s0, s87
	s_addc_u32 s9, s31, 0
	s_mul_i32 s18, s18, s1
	s_mov_b32 s19, 1
	s_mov_b64 s[0:1], 0
	v_mov_b64_e32 v[0:1], s[30:31]
	v_mov_b64_e32 v[2:3], s[2:3]
	v_mov_b64_e32 v[4:5], s[4:5]
	v_mov_b64_e32 v[6:7], s[6:7]
	v_mov_b64_e32 v[8:9], s[8:9]
	s_branch .LBB0_133

.Lewb_1:
	s_and_saveexec_b64 s[36:37], s[2:3]
	s_cbranch_execz .LBB0_222
	s_add_i32 s1, 0, 0x23f00
	v_mov_b32_e32 v0, s1
	s_waitcnt vmcnt(0) expcnt(0) lgkmcnt(0)
	ds_read_b32 v2, v0
	s_add_i32 s1, 0, 0x23f04
	v_mov_b32_e32 v0, s1
	ds_read_b32 v0, v0
	s_waitcnt lgkmcnt(1)
	v_cmp_ne_u32_e32 vcc, 0, v2
	s_cbranch_vccnz .LBB0_193
	v_readlane_b32 s4, v250, 0
	v_readlane_b32 s5, v250, 1
	s_load_dwordx2 s[2:3], s[4:5], 0x4
	s_add_u32 s4, s34, 0x1000
	s_addc_u32 s5, s35, 0
	s_add_u32 s6, s34, 0x1100
	s_addc_u32 s7, s35, 0
	s_add_u32 s8, s34, 0x1200
	s_addc_u32 s9, s35, 0
	s_add_u32 s10, s34, 0x1300
	s_waitcnt lgkmcnt(0)
	s_mul_i32 s1, s2, s87
	s_addc_u32 s11, s35, 0
	s_mul_i32 s1, s1, s3
	s_mov_b32 s20, 1
	s_mov_b64 s[2:3], 0
	v_mov_b64_e32 v[0:1], s[34:35]
	v_mov_b64_e32 v[2:3], s[4:5]
	v_mov_b64_e32 v[4:5], s[6:7]
	v_mov_b64_e32 v[6:7], s[8:9]
	v_mov_b64_e32 v[8:9], s[10:11]
	s_branch .LBB0_183

.Lewb_2:
	s_and_saveexec_b64 s[36:37], s[2:3]
	s_cbranch_execz .LBB0_348
	v_readlane_b32 s1, v255, 24
	s_waitcnt vmcnt(0) expcnt(0) lgkmcnt(0)
	s_nop 0
	v_mov_b32_e32 v0, s1
	ds_read_b32 v2, v0
	v_readlane_b32 s1, v255, 25
	s_waitcnt lgkmcnt(0)
	v_cmp_ne_u32_e32 vcc, 0, v2
	v_mov_b32_e32 v0, s1
	ds_read_b32 v0, v0
	s_cbranch_vccnz .LBB0_319
	v_readlane_b32 s4, v250, 0
	v_readlane_b32 s5, v250, 1
	s_load_dwordx2 s[2:3], s[4:5], 0x4
	s_add_u32 s4, s34, 0x1000
	s_addc_u32 s5, s35, 0
	s_add_u32 s6, s34, 0x1100
	s_addc_u32 s7, s35, 0
	s_add_u32 s8, s34, 0x1200
	s_addc_u32 s9, s35, 0
	s_add_u32 s10, s34, 0x1300
	s_waitcnt lgkmcnt(0)
	s_mul_i32 s1, s2, s87
	s_addc_u32 s11, s35, 0
	s_mul_i32 s1, s1, s3
	s_mov_b32 s20, 1
	s_mov_b64 s[2:3], 0
	v_mov_b64_e32 v[2:3], s[34:35]
	v_mov_b64_e32 v[4:5], s[4:5]
	v_mov_b64_e32 v[6:7], s[6:7]
	v_mov_b64_e32 v[8:9], s[8:9]
	v_mov_b64_e32 v[10:11], s[10:11]
	s_branch .LBB0_309

.Lewb_3:
	s_and_saveexec_b64 s[36:37], s[2:3]
	v_readlane_b32 s38, v255, 42
	s_cbranch_execz .LBB0_435
	v_readlane_b32 s1, v255, 24
	s_waitcnt vmcnt(0) expcnt(0) lgkmcnt(0)
	s_nop 0
	v_mov_b32_e32 v0, s1
	ds_read_b32 v2, v0
	v_readlane_b32 s1, v255, 25
	s_waitcnt lgkmcnt(0)
	v_cmp_ne_u32_e32 vcc, 0, v2
	v_mov_b32_e32 v0, s1
	ds_read_b32 v0, v0
	s_cbranch_vccnz .LBB0_406
	v_readlane_b32 s2, v250, 0
	v_readlane_b32 s3, v250, 1
	s_load_dwordx2 s[6:7], s[2:3], 0x4
	s_add_u32 s2, s34, 0x1000
	s_addc_u32 s3, s35, 0
	s_add_u32 s4, s34, 0x1100
	s_addc_u32 s5, s35, 0
	s_waitcnt lgkmcnt(0)
	s_mul_i32 s1, s6, s87
	s_add_u32 s6, s34, 0x1200
	s_mul_i32 s1, s1, s7
	s_addc_u32 s7, s35, 0
	s_add_u32 s8, s34, 0x1300
	s_addc_u32 s9, s35, 0
	s_mov_b32 s28, 1
	s_mov_b64 s[10:11], 0
	s_branch .LBB0_396

.Lewb_4:
	s_and_saveexec_b64 s[38:39], s[2:3]
	s_cbranch_execz .LBB0_533
	v_readlane_b32 s1, v255, 24
	s_waitcnt vmcnt(0) expcnt(0) lgkmcnt(0)
	s_nop 0
	v_mov_b32_e32 v0, s1
	ds_read_b32 v2, v0
	v_readlane_b32 s1, v255, 25
	s_waitcnt lgkmcnt(0)
	v_cmp_ne_u32_e32 vcc, 0, v2
	v_mov_b32_e32 v0, s1
	ds_read_b32 v0, v0
	s_cbranch_vccnz .LBB0_504
	v_readlane_b32 s2, v250, 0
	v_readlane_b32 s3, v250, 1
	s_load_dwordx2 s[6:7], s[2:3], 0x4
	s_add_u32 s2, s36, 0x1000
	s_addc_u32 s3, s37, 0
	s_add_u32 s4, s36, 0x1100
	s_addc_u32 s5, s37, 0
	s_waitcnt lgkmcnt(0)
	s_mul_i32 s1, s6, s87
	s_add_u32 s6, s36, 0x1200
	s_mul_i32 s1, s1, s7
	s_addc_u32 s7, s37, 0
	s_add_u32 s8, s36, 0x1300
	s_addc_u32 s9, s37, 0
	s_mov_b32 s28, 1
	s_mov_b64 s[10:11], 0
	s_branch .LBB0_494

.Lewb_5:
	s_and_saveexec_b64 s[36:37], s[2:3]
	s_cbranch_execz .LBB0_607
	v_readlane_b32 s1, v255, 24
	s_waitcnt vmcnt(0) expcnt(0) lgkmcnt(0)
	s_nop 0
	v_mov_b32_e32 v0, s1
	ds_read_b32 v2, v0
	v_readlane_b32 s1, v255, 25
	s_waitcnt lgkmcnt(0)
	v_cmp_ne_u32_e32 vcc, 0, v2
	v_mov_b32_e32 v0, s1
	ds_read_b32 v0, v0
	s_cbranch_vccnz .LBB0_578
	v_readlane_b32 s2, v250, 0
	v_readlane_b32 s3, v250, 1
	s_load_dwordx2 s[6:7], s[2:3], 0x4
	s_add_u32 s2, s34, 0x1000
	s_addc_u32 s3, s35, 0
	s_add_u32 s4, s34, 0x1100
	s_addc_u32 s5, s35, 0
	s_waitcnt lgkmcnt(0)
	s_mul_i32 s1, s6, s87
	s_add_u32 s6, s34, 0x1200
	s_mul_i32 s1, s1, s7
	s_addc_u32 s7, s35, 0
	s_add_u32 s8, s34, 0x1300
	s_addc_u32 s9, s35, 0
	s_mov_b32 s28, 1
	s_mov_b64 s[10:11], 0
	s_branch .LBB0_568

.LBB0_1096:
	s_waitcnt vmcnt(0)
	s_barrier
	v_readlane_b32 s96, v250, 44
	s_cmp_eq_u32 s96, 1
	s_cbranch_scc0 .Lewb_7
	buffer_wbl2 sc1
.Lewb_7:
	s_and_saveexec_b64 s[42:43], s[6:7]
	s_cbranch_execz .LBB0_1140
	v_readlane_b32 s1, v255, 24
	s_waitcnt vmcnt(0) expcnt(0) lgkmcnt(0)
	s_nop 0
	v_mov_b32_e32 v0, s1
	ds_read_b32 v2, v0
	v_readlane_b32 s1, v255, 25
	s_waitcnt lgkmcnt(0)
	v_cmp_ne_u32_e32 vcc, 0, v2
	v_mov_b32_e32 v0, s1
	ds_read_b32 v0, v0
	s_cbranch_vccnz .LBB0_1111
	v_readlane_b32 s6, v250, 0
	v_readlane_b32 s7, v250, 1
	s_load_dwordx2 s[10:11], s[6:7], 0x4
	s_add_u32 s6, s40, 0x1000
	s_addc_u32 s7, s41, 0
	s_add_u32 s8, s40, 0x1100
	s_addc_u32 s9, s41, 0
	s_waitcnt lgkmcnt(0)
	s_mul_i32 s1, s10, s87
	s_add_u32 s10, s40, 0x1200
	s_mul_i32 s1, s1, s11
	s_addc_u32 s11, s41, 0
	s_add_u32 s12, s40, 0x1300
	s_addc_u32 s13, s41, 0
	s_mov_b32 s34, 1
	s_mov_b64 s[14:15], 0
	s_branch .LBB0_1101

.Lewb_8:
	s_and_saveexec_b64 s[40:41], s[6:7]
	s_cbranch_execz .LBB0_1210
	v_readlane_b32 s1, v255, 24
	s_waitcnt vmcnt(0) expcnt(0) lgkmcnt(0)
	s_nop 0
	v_mov_b32_e32 v0, s1
	ds_read_b32 v2, v0
	v_readlane_b32 s1, v255, 25
	s_waitcnt lgkmcnt(0)
	v_cmp_ne_u32_e32 vcc, 0, v2
	v_mov_b32_e32 v0, s1
	ds_read_b32 v0, v0
	s_cbranch_vccnz .LBB0_1181
	v_readlane_b32 s6, v250, 0
	v_readlane_b32 s7, v250, 1
	s_load_dwordx2 s[10:11], s[6:7], 0x4
	s_add_u32 s6, s38, 0x1000
	s_addc_u32 s7, s39, 0
	s_add_u32 s8, s38, 0x1100
	s_addc_u32 s9, s39, 0
	s_waitcnt lgkmcnt(0)
	s_mul_i32 s1, s10, s87
	s_add_u32 s10, s38, 0x1200
	s_mul_i32 s1, s1, s11
	s_addc_u32 s11, s39, 0
	s_add_u32 s12, s38, 0x1300
	s_addc_u32 s13, s39, 0
	s_mov_b32 s34, 1
	s_mov_b64 s[14:15], 0
	s_branch .LBB0_1171

.Lewb_9:
	s_and_saveexec_b64 s[30:31], s[0:1]
	v_readlane_b32 s40, v250, 40
	v_readlane_b32 s38, v250, 38
	v_readlane_b32 s34, v251, 7
	v_readlane_b32 s36, v251, 9
	v_readlane_b32 s41, v250, 41
	v_readlane_b32 s42, v250, 42
	v_readlane_b32 s43, v250, 43
	v_readlane_b32 s39, v250, 39
	v_readlane_b32 s35, v251, 8
	v_readlane_b32 s37, v251, 10
	s_cbranch_execz .LBB0_1377
	s_add_i32 s0, 0, 0x23f00
	v_mov_b32_e32 v0, s0
	s_waitcnt vmcnt(0) expcnt(0) lgkmcnt(0)
	ds_read_b32 v2, v0
	s_add_i32 s0, 0, 0x23f04
	v_mov_b32_e32 v0, s0
	ds_read_b32 v0, v0
	s_waitcnt lgkmcnt(1)
	v_cmp_ne_u32_e32 vcc, 0, v2
	s_cbranch_vccnz .LBB0_1348
	v_readlane_b32 s2, v250, 0
	v_readlane_b32 s3, v250, 1
	v_readlane_b32 s10, v250, 3
	s_load_dwordx2 s[0:1], s[2:3], 0x4
	v_readlane_b32 s11, v250, 4
	s_add_u32 s2, s10, 0x1000
	s_addc_u32 s3, s11, 0
	s_add_u32 s4, s10, 0x1100
	s_addc_u32 s5, s11, 0
	s_add_u32 s6, s10, 0x1200
	s_addc_u32 s7, s11, 0
	s_add_u32 s8, s10, 0x1300
	s_waitcnt lgkmcnt(0)
	s_mul_i32 s18, s0, s87
	s_addc_u32 s9, s11, 0
	s_mul_i32 s18, s18, s1
	s_mov_b32 s19, 1
	s_mov_b64 s[0:1], 0
	v_mov_b64_e32 v[0:1], s[10:11]
	v_mov_b64_e32 v[2:3], s[2:3]
	v_mov_b64_e32 v[4:5], s[4:5]
	v_mov_b64_e32 v[6:7], s[6:7]
	v_mov_b64_e32 v[8:9], s[8:9]
	s_branch .LBB0_1338
